# branch GEMMs: the 8 fifth-round units of BR-B moved from workgroups 0-7 to 8-15 (flag release/acquire on the BR-A result), balancing the two back-to-back phases
# speedup vs baseline: 1.0043x; 1.0026x over previous
_Z14fwd_megakernel4Args:
	s_add_u32 s8, s0, 0xe0
	s_addc_u32 s9, s1, 0
	s_load_dwordx2 s[34:35], s[0:1], 0xe0
	s_load_dword s78, s[0:1], 0xe8
	s_load_dwordx2 s[10:11], s[0:1], 0xd8
	v_and_b32_e32 v194, 0x3ff, v0
	v_cmp_gt_u32_e32 vcc, 2, v194
	s_and_saveexec_b64 s[4:5], vcc
	v_lshl_add_u32 v1, v194, 2, 0
	v_add_u32_e32 v1, 0x27fc0, v1
	v_mov_b32_e32 v2, 0
	ds_write_b32 v1, v2
	s_or_b64 exec, exec, s[4:5]
	s_cmp_eq_u32 s2, 0
	s_cselect_b64 s[6:7], -1, 0
	s_cmp_lg_u32 s2, 0
	s_mov_b32 s12, 0
	s_cbranch_scc0 .LBB0_127
	v_cmp_gt_u32_e32 vcc, 16, v194
	s_and_b64 s[6:7], s[6:7], vcc
	s_and_saveexec_b64 s[4:5], s[6:7]
	s_cbranch_execz .LBB0_5

.LBB0_133:
	s_or_b64 exec, exec, s[16:17]
	v_cmp_gt_u32_e32 vcc, 16, v194
	s_and_b64 s[6:7], s[6:7], vcc
	s_and_saveexec_b64 s[4:5], s[6:7]
	s_cbranch_execnz .LBB0_4
	s_branch .LBB0_5

.LBB0_1366:
	s_load_dwordx4 s[8:11], s[0:1], 0xd0
	s_mov_b32 s98, 0
	s_mov_b32 s99, 0
	s_cmp_lt_u32 s2, 8
	s_cbranch_scc0 .Lbr_nosig
	v_readfirstlane_b32 s100, v194
	s_cmp_lt_u32 s100, 64
	s_cbranch_scc0 .Lbr_nosig
	s_waitcnt lgkmcnt(0)
	buffer_wbl2 sc1
	s_waitcnt vmcnt(0)
	s_lshl_b32 s100, s2, 8
	s_add_u32 s100, s10, s100
	s_addc_u32 s101, s11, 0
	s_add_u32 s100, s100, 0x14800
	s_addc_u32 s101, s101, 0
	v_mov_b32_e32 v249, 0
	v_mov_b32_e32 v250, 1
	global_store_dword v249, v250, s[100:101] sc0 sc1
	s_waitcnt vmcnt(0)
.Lbr_nosig:
	v_mov_b32_e32 v9, v194
	s_and_b64 vcc, exec, s[4:5]
	v_readfirstlane_b32 s7, v9
	s_cbranch_vccnz .LBB0_1382
	v_lshlrev_b32_e32 v0, 4, v9
	v_add_u32_e32 v1, 0x2000, v0
	v_ashrrev_i32_e32 v2, 31, v1
	v_lshrrev_b32_e32 v2, 22, v2
	v_add_u32_e32 v2, v1, v2
	v_ashrrev_i32_e32 v8, 10, v2
	v_mul_i32_i24_e32 v2, 0x400, v8
	v_sub_u32_e32 v1, v1, v2
	v_lshrrev_b32_e32 v2, 4, v1
	v_bitop3_b32 v1, v2, v1, 32 bitop3:0x6c
	v_ashrrev_i32_e32 v2, 31, v1
	v_lshrrev_b32_e32 v2, 26, v2
	v_add_u32_e32 v2, v1, v2
	v_lshlrev_b32_e32 v3, 3, v8
	v_ashrrev_i32_e32 v10, 6, v2
	v_and_b32_e32 v3, -16, v3
	v_add_u32_e32 v3, v10, v3
	v_and_b32_e32 v4, 3, v10
	s_mov_b32 s6, 0x1fffe0
	v_lshrrev_b32_e32 v5, 2, v3
	v_lshlrev_b32_e32 v6, 1, v3
	v_and_b32_e32 v2, 0xc0, v2
	v_and_or_b32 v4, v3, s6, v4
	v_and_b32_e32 v5, 4, v5
	v_and_b32_e32 v6, 24, v6
	v_sub_u32_e32 v1, v1, v2
	v_mov_b32_e32 v2, 1
	v_or3_b32 v4, v4, v5, v6
	v_lshlrev_b32_e32 v5, 5, v8
	v_ashrrev_i16_sdwa v1, v2, sext(v1) dst_sel:DWORD dst_unused:UNUSED_PAD src0_sel:DWORD src1_sel:BYTE_0
	v_and_b32_e32 v5, 32, v5
	v_bfe_i32 v11, v1, 0, 16
	v_add_lshl_u32 v1, v5, v11, 1
	v_lshl_add_u32 v152, v4, 11, v1
	v_lshl_add_u32 v154, v3, 11, v1
	v_bfe_i32 v1, v9, 27, 1
	v_lshrrev_b32_e32 v1, 22, v1
	v_add_u32_e32 v1, v0, v1
	v_and_b32_e32 v1, 0xfffffc00, v1
	v_sub_u32_e32 v0, v0, v1
	v_lshrrev_b32_e32 v1, 4, v0
	v_ashrrev_i32_e32 v3, 31, v9
	v_bitop3_b32 v0, v1, v0, 32 bitop3:0x6c
	v_lshrrev_b32_e32 v3, 26, v3
	v_ashrrev_i32_e32 v1, 31, v0
	v_add_u32_e32 v3, v9, v3
	s_waitcnt lgkmcnt(0)
	s_add_u32 s3, s10, 0x1eb00000
	v_lshrrev_b32_e32 v1, 26, v1
	v_ashrrev_i32_e32 v13, 6, v3
	s_addc_u32 s31, s11, 0
	v_add_u32_e32 v1, v0, v1
	v_lshlrev_b32_e32 v3, 3, v13
	s_add_u32 s40, s10, 0x3200000
	v_ashrrev_i32_e32 v12, 6, v1
	v_and_b32_e32 v3, -16, v3
	s_addc_u32 s41, s11, 0
	v_add_u32_e32 v3, v12, v3
	v_and_b32_e32 v4, 3, v12
	s_ashr_i32 s47, s2, 31
	v_and_or_b32 v4, v3, s6, v4
	s_lshr_b32 s6, s47, 29
	s_add_i32 s6, s2, s6
	s_ashr_i32 s16, s7, 6
	s_ashr_i32 s12, s6, 3
	s_and_b32 s6, s6, -8
	s_ashr_i32 s18, s7, 8
	s_lshl_b32 s46, s16, 10
	s_sub_i32 s6, s2, s6
	s_cmp_lt_i32 s6, 0
	s_movk_i32 s48, 0x82
	s_cselect_b32 s13, s48, 0x81
	s_mul_i32 s6, s6, s13
	s_add_i32 s6, s6, s12
	s_ashr_i32 s12, s6, 31
	s_lshr_b32 s12, s12, 27
	s_add_i32 s12, s6, s12
	v_lshrrev_b32_e32 v5, 2, v3
	v_lshlrev_b32_e32 v6, 1, v3
	v_and_b32_e32 v1, 0xc0, v1
	s_ashr_i32 s12, s12, 5
	v_and_b32_e32 v5, 4, v5
	v_and_b32_e32 v6, 24, v6
	v_sub_u32_e32 v0, v0, v1
	s_lshl_b32 s14, s12, 3
	v_or3_b32 v4, v4, v5, v6
	v_lshlrev_b32_e32 v5, 5, v13
	v_ashrrev_i16_sdwa v0, v2, sext(v0) dst_sel:DWORD dst_unused:UNUSED_PAD src0_sel:DWORD src1_sel:BYTE_0
	s_sub_i32 s13, 0x102, s14
	s_lshl_b32 s12, s12, 5
	v_and_b32_e32 v5, 32, v5
	v_bfe_i32 v14, v0, 0, 16
	s_min_u32 s15, s13, 8
	s_sub_i32 s17, s6, s12
	v_add_lshl_u32 v0, v5, v14, 1
	s_sext_i32_i8 s6, s17
	v_cvt_f32_ubyte0_e32 v2, s15
	v_lshl_add_u32 v156, v4, 11, v0
	v_cvt_f32_i32_e32 v1, s6
	v_rcp_iflag_f32_e32 v4, v2
	v_lshl_add_u32 v158, v3, 11, v0
	s_ashr_i32 s6, s6, 30
	s_or_b32 s6, s6, 1
	v_mul_f32_e32 v0, v1, v4
	v_trunc_f32_e32 v0, v0
	v_fma_f32 v1, -v0, v2, v1
	v_cvt_i32_f32_e32 v0, v0
	v_cmp_ge_f32_e64 s[12:13], |v1|, v2
	s_and_b64 s[12:13], s[12:13], exec
	s_cselect_b32 s6, s6, 0
	v_readfirstlane_b32 s12, v0
	s_add_i32 s6, s12, s6
	s_mul_i32 s12, s6, s15
	s_sub_i32 s12, s17, s12
	s_sext_i32_i8 s12, s12
	s_add_i32 s36, s14, s12
	s_ashr_i32 s37, s36, 31
	s_bfe_i64 s[14:15], s[6:7], 0x80000
	s_lshl_b64 s[12:13], s[36:37], 19
	s_lshl_b64 s[14:15], s[14:15], 19
	s_add_u32 s42, s40, s14
	s_addc_u32 s43, s41, s15
	s_add_i32 s37, s46, 0
	s_add_i32 m0, s37, 0x10000
	v_mov_b32_e32 v157, 0
	global_load_lds_dwordx4 v156, s[42:43]
	s_add_i32 m0, s37, 0x12000
	s_add_u32 s14, s42, 0x40000
	global_load_lds_dwordx4 v152, s[42:43]
	s_addc_u32 s15, s43, 0
	s_add_i32 m0, s37, 0x14000
	v_mov_b32_e32 v153, v157
	global_load_lds_dwordx4 v156, s[14:15]
	s_add_i32 m0, s37, 0x16000
	s_add_u32 s38, s3, s12
	s_addc_u32 s39, s31, s13
	s_add_i32 s49, s37, 0x2000
	global_load_lds_dwordx4 v152, s[14:15]
	s_mov_b32 m0, s37
	s_add_u32 s12, s38, 0x40000
	global_load_lds_dwordx4 v158, s[38:39]
	s_mov_b32 m0, s49
	s_addc_u32 s13, s39, 0
	s_add_i32 s50, s37, 0x4000
	global_load_lds_dwordx4 v154, s[38:39]
	s_mov_b32 m0, s50
	s_add_i32 s51, s37, 0x6000
	global_load_lds_dwordx4 v158, s[12:13]
	s_mov_b32 m0, s51
	v_mov_b32_e32 v159, v157
	global_load_lds_dwordx4 v154, s[12:13]
	v_mov_b32_e32 v155, v157
	s_cmp_eq_u32 s18, 1
	s_mov_b32 s52, 0
	v_lshl_add_u64 v[6:7], s[42:43], 0, v[156:157]
	v_lshl_add_u64 v[4:5], s[42:43], 0, v[152:153]
	v_lshl_add_u64 v[0:1], s[38:39], 0, v[158:159]
	s_cselect_b64 s[12:13], -1, 0
	s_cmp_lg_u32 s18, 1
	v_lshl_add_u64 v[2:3], s[38:39], 0, v[154:155]
	s_cbranch_scc1 .LBB0_1369
	s_barrier

.LBB0_1372:
	s_add_i32 s52, s52, 1
	s_mul_i32 s6, s52, s55
	s_mul_hi_u32 s7, s52, s56
	s_add_i32 s7, s7, s6
	s_mul_i32 s6, s52, s56
	s_add_u32 s24, s6, s2
	s_addc_u32 s25, s7, s47
	s_mov_b32 s99, s98
	s_cmp_ge_u32 s24, 0x400
	s_cselect_b32 s98, 8, 0
	s_xor_b32 s24, s24, s98
	v_cmp_gt_i64_e32 vcc, s[24:25], v[166:167]
	v_cmp_lt_i64_e64 s[6:7], s[24:25], v[164:165]
	s_cbranch_vccnz .LBB0_1374
	s_ashr_i32 s20, s24, 31
	s_lshr_b32 s20, s20, 29
	s_add_i32 s20, s24, s20
	s_ashr_i32 s21, s20, 3
	s_and_b32 s20, s20, -8
	s_sub_i32 s20, s24, s20
	s_cmp_lt_i32 s20, 0
	s_cselect_b32 s22, s48, 0x81
	s_mul_i32 s20, s20, s22
	s_add_i32 s20, s20, s21
	s_ashr_i32 s21, s20, 31
	s_lshr_b32 s21, s21, 27
	s_add_i32 s21, s20, s21
	s_ashr_i32 s22, s21, 5
	s_lshl_b32 s22, s22, 3
	s_sub_i32 s23, 0x102, s22
	s_min_i32 s23, s23, 8
	s_abs_i32 s24, s23
	v_cvt_f32_u32_e32 v0, s24
	s_sub_i32 s26, 0, s24
	s_andn2_b32 s21, s21, 31
	s_sub_i32 s21, s20, s21
	v_rcp_iflag_f32_e32 v0, v0
	s_abs_i32 s20, s21
	s_xor_b32 s25, s21, s23
	s_ashr_i32 s25, s25, 31
	v_mul_f32_e32 v0, 0x4f7ffffe, v0
	v_cvt_u32_f32_e32 v0, v0
	s_nop 0
	v_readfirstlane_b32 s27, v0
	s_mul_i32 s26, s26, s27
	s_mul_hi_u32 s26, s27, s26
	s_add_i32 s27, s27, s26
	s_mul_hi_u32 s26, s20, s27
	s_mul_i32 s27, s26, s24
	s_sub_i32 s20, s20, s27
	s_add_i32 s44, s26, 1
	s_sub_i32 s27, s20, s24
	s_cmp_ge_u32 s20, s24
	s_cselect_b32 s26, s44, s26
	s_cselect_b32 s20, s27, s20
	s_add_i32 s27, s26, 1
	s_cmp_ge_u32 s20, s24
	s_cselect_b32 s20, s27, s26
	s_xor_b32 s20, s20, s25
	s_sub_i32 s20, s20, s25
	s_mul_i32 s23, s20, s23
	s_sub_i32 s21, s21, s23
	s_add_i32 s22, s22, s21

.LBB0_1378:
	s_cmp_eq_u32 s99, 0
	s_cbranch_scc1 .Lbr_nowait
	s_lshl_b32 s100, s2, 8
	s_add_u32 s100, s10, s100
	s_addc_u32 s101, s11, 0
	s_add_u32 s100, s100, 0x14000
	s_addc_u32 s101, s101, 0
	v_mov_b32_e32 v249, 0
	v_mov_b32_e32 v251, 0
.Lbr_spin:
	global_load_dword v250, v249, s[100:101] sc0 sc1
	s_waitcnt vmcnt(0)
	v_add_u32_e32 v251, 1, v251
	v_cmp_eq_u32_e32 vcc, 1, v250
	s_nop 1
	s_cbranch_vccnz .Lbr_got
	s_sleep 2
	v_cmp_gt_u32_e32 vcc, 0x4000, v251
	s_nop 1
	s_cbranch_vccnz .Lbr_spin
.Lbr_got:
	buffer_inv sc1
.Lbr_nowait:
	v_lshl_add_u32 v172, s36, 8, v178
	v_lshl_or_b32 v170, s59, 8, v180
	v_ashrrev_i32_e32 v173, 31, v172
	v_ashrrev_i32_e32 v171, 31, v170
	v_lshlrev_b64 v[128:129], 10, v[172:173]
	v_lshl_add_u64 v[128:129], v[128:129], 0, v[170:171]
	v_lshlrev_b64 v[128:129], 1, v[128:129]
	v_lshl_add_u64 v[130:131], s[8:9], 0, v[128:129]
	global_load_dwordx4 v[186:189], v[130:131], off
	v_lshl_add_u64 v[130:131], s[14:15], 0, v[128:129]
	global_load_dwordx4 v[190:193], v[130:131], off
	v_or_b32_e32 v128, 0x100, v128
	v_or_b32_e32 v228, 16, v172
	v_lshl_add_u64 v[130:131], s[8:9], 0, v[128:129]
	v_lshl_add_u64 v[128:129], s[14:15], 0, v[128:129]
	v_ashrrev_i32_e32 v229, 31, v228
	global_load_dwordx4 v[196:199], v[130:131], off
	global_load_dwordx4 v[200:203], v[128:129], off
	v_lshlrev_b64 v[130:131], 10, v[228:229]
	v_lshl_add_u64 v[130:131], v[130:131], 0, v[170:171]
	v_lshlrev_b64 v[130:131], 1, v[130:131]
	v_lshl_add_u64 v[136:137], s[8:9], 0, v[130:131]
	global_load_dwordx4 v[204:207], v[136:137], off
	v_lshl_add_u64 v[136:137], s[14:15], 0, v[130:131]
	global_load_dwordx4 v[208:211], v[136:137], off
	v_or_b32_e32 v176, 32, v172
	v_or_b32_e32 v174, 48, v172
	v_ashrrev_i32_e32 v177, 31, v176
	v_ashrrev_i32_e32 v175, 31, v174
	v_lshlrev_b64 v[128:129], 11, v[172:173]
	v_lshlrev_b64 v[132:133], 10, v[176:177]
	v_lshlrev_b64 v[168:169], 1, v[170:171]
	v_lshlrev_b64 v[134:135], 10, v[174:175]
	v_lshl_add_u64 v[128:129], s[14:15], 0, v[128:129]
	v_lshl_add_u64 v[132:133], v[132:133], 0, v[170:171]
	v_lshl_add_u64 v[134:135], v[134:135], 0, v[170:171]
	v_lshl_add_u64 v[230:231], v[128:129], 0, v[168:169]
	v_lshlrev_b64 v[128:129], 1, v[132:133]
	v_lshlrev_b64 v[132:133], 1, v[134:135]
	v_or_b32_e32 v130, 0x100, v130
	v_lshl_add_u64 v[134:135], s[8:9], 0, v[128:129]
	v_lshl_add_u64 v[136:137], s[14:15], 0, v[128:129]
	v_or_b32_e32 v128, 0x100, v128
	v_lshl_add_u64 v[138:139], s[8:9], 0, v[132:133]
	v_lshl_add_u64 v[144:145], s[14:15], 0, v[132:133]
	v_or_b32_e32 v132, 0x100, v132
	v_lshl_add_u64 v[146:147], s[8:9], 0, v[130:131]
	v_lshl_add_u64 v[130:131], s[14:15], 0, v[130:131]
	global_load_dwordx4 v[212:215], v[134:135], off
	global_load_dwordx4 v[216:219], v[136:137], off
	v_lshl_add_u64 v[134:135], s[8:9], 0, v[128:129]
	v_lshl_add_u64 v[128:129], s[14:15], 0, v[128:129]
	global_load_dwordx4 v[140:143], v[138:139], off
	s_nop 0
	global_load_dwordx4 v[136:139], v[144:145], off
	v_lshl_add_u64 v[232:233], s[8:9], 0, v[132:133]
	v_lshl_add_u64 v[234:235], s[14:15], 0, v[132:133]
	global_load_dwordx4 v[220:223], v[146:147], off
	global_load_dwordx4 v[224:227], v[130:131], off
	global_load_dwordx4 v[148:151], v[134:135], off
	s_nop 0
	global_load_dwordx4 v[144:147], v[128:129], off
	global_load_dwordx4 v[132:135], v[232:233], off
	s_nop 0
	global_load_dwordx4 v[128:131], v[234:235], off
	s_andn2_b64 vcc, exec, s[6:7]
	s_mov_b64 s[6:7], -1
	s_waitcnt vmcnt(0)
	v_lshlrev_b32_e32 v232, 16, v186
	v_and_b32_e32 v233, 0xffff0000, v186
	v_lshlrev_b32_e32 v234, 16, v190
	v_and_b32_e32 v235, 0xffff0000, v190
	v_lshlrev_b32_e32 v186, 16, v187
	v_and_b32_e32 v187, 0xffff0000, v187
	v_lshlrev_b32_e32 v190, 16, v191
	v_and_b32_e32 v191, 0xffff0000, v191
	v_lshlrev_b32_e32 v236, 16, v188
	v_and_b32_e32 v237, 0xffff0000, v188
	v_lshlrev_b32_e32 v238, 16, v192
	v_and_b32_e32 v239, 0xffff0000, v192
	v_lshlrev_b32_e32 v188, 16, v189
	v_and_b32_e32 v189, 0xffff0000, v189
	v_lshlrev_b32_e32 v192, 16, v193
	v_and_b32_e32 v193, 0xffff0000, v193
	v_pk_fma_f32 v[124:125], v[124:125], v[232:233], v[234:235]
	v_pk_fma_f32 v[126:127], v[126:127], v[186:187], v[190:191]
	v_pk_fma_f32 v[186:187], v[120:121], v[236:237], v[238:239]
	v_pk_fma_f32 v[188:189], v[122:123], v[188:189], v[192:193]
	v_cvt_pk_bf16_f32 v120, v124, v125
	v_cvt_pk_bf16_f32 v121, v126, v127
	v_cvt_pk_bf16_f32 v122, v186, v187
	v_cvt_pk_bf16_f32 v123, v188, v189
	global_store_dwordx4 v[230:231], v[120:123], off
	v_lshlrev_b32_e32 v190, 16, v196
	v_and_b32_e32 v191, 0xffff0000, v196
	v_lshlrev_b32_e32 v120, 16, v197
	v_and_b32_e32 v121, 0xffff0000, v197
	v_lshlrev_b32_e32 v122, 16, v201
	v_and_b32_e32 v123, 0xffff0000, v201
	v_pk_fma_f32 v[118:119], v[118:119], v[120:121], v[122:123]
	v_lshlrev_b32_e32 v120, 16, v198
	v_and_b32_e32 v121, 0xffff0000, v198
	v_lshlrev_b32_e32 v122, 16, v202
	v_and_b32_e32 v123, 0xffff0000, v202
	v_lshlrev_b32_e32 v192, 16, v200
	v_and_b32_e32 v193, 0xffff0000, v200
	v_pk_fma_f32 v[120:121], v[112:113], v[120:121], v[122:123]
	v_lshlrev_b32_e32 v112, 16, v199
	v_and_b32_e32 v113, 0xffff0000, v199
	v_lshlrev_b32_e32 v122, 16, v203
	v_and_b32_e32 v123, 0xffff0000, v203
	v_pk_fma_f32 v[116:117], v[116:117], v[190:191], v[192:193]
	v_pk_fma_f32 v[122:123], v[114:115], v[112:113], v[122:123]
	v_cvt_pk_bf16_f32 v112, v116, v117
	v_cvt_pk_bf16_f32 v113, v118, v119
	v_cvt_pk_bf16_f32 v114, v120, v121
	v_cvt_pk_bf16_f32 v115, v122, v123
	global_store_dwordx4 v[230:231], v[112:115], off offset:256
	v_lshlrev_b32_e32 v116, 16, v208
	v_and_b32_e32 v117, 0xffff0000, v208
	v_lshlrev_b32_e32 v114, 16, v204
	v_and_b32_e32 v115, 0xffff0000, v204
	v_pk_fma_f32 v[108:109], v[108:109], v[114:115], v[116:117]
	v_lshlrev_b32_e32 v114, 16, v205
	v_and_b32_e32 v115, 0xffff0000, v205
	v_lshlrev_b32_e32 v116, 16, v209
	v_and_b32_e32 v117, 0xffff0000, v209
	v_pk_fma_f32 v[110:111], v[110:111], v[114:115], v[116:117]
	v_lshlrev_b32_e32 v114, 16, v206
	v_and_b32_e32 v115, 0xffff0000, v206
	v_lshlrev_b32_e32 v116, 16, v210
	v_and_b32_e32 v117, 0xffff0000, v210
	v_lshlrev_b64 v[112:113], 11, v[228:229]
	v_pk_fma_f32 v[114:115], v[104:105], v[114:115], v[116:117]
	v_lshlrev_b32_e32 v104, 16, v207
	v_and_b32_e32 v105, 0xffff0000, v207
	v_lshlrev_b32_e32 v116, 16, v211
	v_and_b32_e32 v117, 0xffff0000, v211
	v_pk_fma_f32 v[116:117], v[106:107], v[104:105], v[116:117]
	v_cvt_pk_bf16_f32 v104, v108, v109
	v_lshl_add_u64 v[108:109], s[14:15], 0, v[112:113]
	v_cvt_pk_bf16_f32 v105, v110, v111
	v_cvt_pk_bf16_f32 v106, v114, v115
	v_cvt_pk_bf16_f32 v107, v116, v117
	v_lshl_add_u64 v[108:109], v[108:109], 0, v[168:169]
	global_store_dwordx4 v[108:109], v[104:107], off
	s_nop 1
	v_lshlrev_b32_e32 v104, 16, v220
	v_and_b32_e32 v105, 0xffff0000, v220
	v_lshlrev_b32_e32 v106, 16, v224
	v_and_b32_e32 v107, 0xffff0000, v224
	v_pk_fma_f32 v[100:101], v[100:101], v[104:105], v[106:107]
	v_lshlrev_b32_e32 v104, 16, v221
	v_and_b32_e32 v105, 0xffff0000, v221
	v_lshlrev_b32_e32 v106, 16, v225
	v_and_b32_e32 v107, 0xffff0000, v225
	v_pk_fma_f32 v[102:103], v[102:103], v[104:105], v[106:107]
	v_lshlrev_b32_e32 v104, 16, v222
	v_and_b32_e32 v105, 0xffff0000, v222
	v_lshlrev_b32_e32 v106, 16, v226
	v_and_b32_e32 v107, 0xffff0000, v226
	v_pk_fma_f32 v[104:105], v[96:97], v[104:105], v[106:107]
	v_lshlrev_b32_e32 v96, 16, v223
	v_and_b32_e32 v97, 0xffff0000, v223
	v_lshlrev_b32_e32 v106, 16, v227
	v_and_b32_e32 v107, 0xffff0000, v227
	v_pk_fma_f32 v[106:107], v[98:99], v[96:97], v[106:107]
	v_cvt_pk_bf16_f32 v96, v100, v101
	v_cvt_pk_bf16_f32 v97, v102, v103
	v_cvt_pk_bf16_f32 v98, v104, v105
	v_cvt_pk_bf16_f32 v99, v106, v107
	global_store_dwordx4 v[108:109], v[96:99], off offset:256
	v_lshlrev_b32_e32 v100, 16, v216
	v_and_b32_e32 v101, 0xffff0000, v216
	v_lshlrev_b32_e32 v98, 16, v212
	v_and_b32_e32 v99, 0xffff0000, v212
	v_pk_fma_f32 v[92:93], v[92:93], v[98:99], v[100:101]
	v_lshlrev_b32_e32 v98, 16, v213
	v_and_b32_e32 v99, 0xffff0000, v213
	v_lshlrev_b32_e32 v100, 16, v217
	v_and_b32_e32 v101, 0xffff0000, v217
	v_pk_fma_f32 v[94:95], v[94:95], v[98:99], v[100:101]
	v_lshlrev_b32_e32 v98, 16, v214
	v_and_b32_e32 v99, 0xffff0000, v214
	v_lshlrev_b32_e32 v100, 16, v218
	v_and_b32_e32 v101, 0xffff0000, v218
	v_lshlrev_b64 v[96:97], 11, v[176:177]
	v_pk_fma_f32 v[98:99], v[88:89], v[98:99], v[100:101]
	v_lshlrev_b32_e32 v88, 16, v215
	v_and_b32_e32 v89, 0xffff0000, v215
	v_lshlrev_b32_e32 v100, 16, v219
	v_and_b32_e32 v101, 0xffff0000, v219
	v_pk_fma_f32 v[100:101], v[90:91], v[88:89], v[100:101]
	v_cvt_pk_bf16_f32 v88, v92, v93
	v_lshl_add_u64 v[92:93], s[14:15], 0, v[96:97]
	v_cvt_pk_bf16_f32 v89, v94, v95
	v_cvt_pk_bf16_f32 v90, v98, v99
	v_cvt_pk_bf16_f32 v91, v100, v101
	v_lshl_add_u64 v[92:93], v[92:93], 0, v[168:169]
	global_store_dwordx4 v[92:93], v[88:91], off
	v_add_u32_e32 v96, 0xb0, v172
	v_ashrrev_i32_e32 v97, 31, v96
	v_lshlrev_b32_e32 v88, 16, v148
	v_and_b32_e32 v89, 0xffff0000, v148
	v_lshlrev_b32_e32 v90, 16, v144
	v_and_b32_e32 v91, 0xffff0000, v144
	v_pk_fma_f32 v[84:85], v[84:85], v[88:89], v[90:91]
	v_lshlrev_b32_e32 v88, 16, v149
	v_and_b32_e32 v89, 0xffff0000, v149
	v_lshlrev_b32_e32 v90, 16, v145
	v_and_b32_e32 v91, 0xffff0000, v145
	v_pk_fma_f32 v[86:87], v[86:87], v[88:89], v[90:91]
	v_lshlrev_b32_e32 v88, 16, v150
	v_and_b32_e32 v89, 0xffff0000, v150
	v_lshlrev_b32_e32 v90, 16, v146
	v_and_b32_e32 v91, 0xffff0000, v146
	v_pk_fma_f32 v[88:89], v[80:81], v[88:89], v[90:91]
	v_lshlrev_b32_e32 v80, 16, v151
	v_and_b32_e32 v81, 0xffff0000, v151
	v_lshlrev_b32_e32 v90, 16, v147
	v_and_b32_e32 v91, 0xffff0000, v147
	v_pk_fma_f32 v[90:91], v[82:83], v[80:81], v[90:91]
	v_cvt_pk_bf16_f32 v80, v84, v85
	v_cvt_pk_bf16_f32 v81, v86, v87
	v_cvt_pk_bf16_f32 v82, v88, v89
	v_cvt_pk_bf16_f32 v83, v90, v91
	global_store_dwordx4 v[92:93], v[80:83], off offset:256
	v_lshlrev_b32_e32 v84, 16, v136
	v_and_b32_e32 v85, 0xffff0000, v136
	v_lshlrev_b32_e32 v82, 16, v140
	v_and_b32_e32 v83, 0xffff0000, v140
	v_pk_fma_f32 v[76:77], v[76:77], v[82:83], v[84:85]
	v_lshlrev_b32_e32 v82, 16, v141
	v_and_b32_e32 v83, 0xffff0000, v141
	v_lshlrev_b32_e32 v84, 16, v137
	v_and_b32_e32 v85, 0xffff0000, v137
	v_pk_fma_f32 v[78:79], v[78:79], v[82:83], v[84:85]
	v_lshlrev_b32_e32 v82, 16, v142
	v_and_b32_e32 v83, 0xffff0000, v142
	v_lshlrev_b32_e32 v84, 16, v138
	v_and_b32_e32 v85, 0xffff0000, v138
	v_lshlrev_b64 v[80:81], 11, v[174:175]
	v_pk_fma_f32 v[82:83], v[72:73], v[82:83], v[84:85]
	v_lshlrev_b32_e32 v72, 16, v143
	v_and_b32_e32 v73, 0xffff0000, v143
	v_lshlrev_b32_e32 v84, 16, v139
	v_and_b32_e32 v85, 0xffff0000, v139
	v_pk_fma_f32 v[84:85], v[74:75], v[72:73], v[84:85]
	v_cvt_pk_bf16_f32 v72, v76, v77
	v_lshl_add_u64 v[76:77], s[14:15], 0, v[80:81]
	v_cvt_pk_bf16_f32 v73, v78, v79
	v_cvt_pk_bf16_f32 v74, v82, v83
	v_cvt_pk_bf16_f32 v75, v84, v85
	v_lshl_add_u64 v[76:77], v[76:77], 0, v[168:169]
	global_store_dwordx4 v[76:77], v[72:75], off
	s_nop 1
	v_lshlrev_b32_e32 v72, 16, v132
	v_and_b32_e32 v73, 0xffff0000, v132
	v_lshlrev_b32_e32 v74, 16, v128
	v_and_b32_e32 v75, 0xffff0000, v128
	v_pk_fma_f32 v[68:69], v[68:69], v[72:73], v[74:75]
	v_lshlrev_b32_e32 v72, 16, v133
	v_and_b32_e32 v73, 0xffff0000, v133
	v_lshlrev_b32_e32 v74, 16, v129
	v_and_b32_e32 v75, 0xffff0000, v129
	v_pk_fma_f32 v[70:71], v[70:71], v[72:73], v[74:75]
	v_lshlrev_b32_e32 v72, 16, v134
	v_and_b32_e32 v73, 0xffff0000, v134
	v_lshlrev_b32_e32 v74, 16, v130
	v_and_b32_e32 v75, 0xffff0000, v130
	v_pk_fma_f32 v[72:73], v[64:65], v[72:73], v[74:75]
	v_lshlrev_b32_e32 v64, 16, v135
	v_and_b32_e32 v65, 0xffff0000, v135
	v_lshlrev_b32_e32 v74, 16, v131
	v_and_b32_e32 v75, 0xffff0000, v131
	v_pk_fma_f32 v[74:75], v[66:67], v[64:65], v[74:75]
	v_add_u32_e32 v130, 0x80, v172
	v_cvt_pk_bf16_f32 v64, v68, v69
	v_cvt_pk_bf16_f32 v65, v70, v71
	v_cvt_pk_bf16_f32 v66, v72, v73
	v_cvt_pk_bf16_f32 v67, v74, v75
	v_ashrrev_i32_e32 v131, 31, v130
	global_store_dwordx4 v[76:77], v[64:67], off offset:256
	v_add_u32_e32 v132, 0x90, v172
	v_ashrrev_i32_e32 v133, 31, v132
	v_lshlrev_b64 v[64:65], 10, v[130:131]
	v_lshl_add_u64 v[64:65], v[64:65], 0, v[170:171]
	v_lshlrev_b64 v[64:65], 1, v[64:65]
	v_lshl_add_u64 v[66:67], s[8:9], 0, v[64:65]
	global_load_dwordx4 v[98:101], v[66:67], off
	v_lshl_add_u64 v[66:67], s[14:15], 0, v[64:65]
	global_load_dwordx4 v[102:105], v[66:67], off
	v_or_b32_e32 v64, 0x100, v64
	v_lshl_add_u64 v[66:67], s[8:9], 0, v[64:65]
	v_lshl_add_u64 v[64:65], s[14:15], 0, v[64:65]
	global_load_dwordx4 v[106:109], v[66:67], off
	global_load_dwordx4 v[110:113], v[64:65], off
	v_lshlrev_b64 v[64:65], 10, v[132:133]
	v_lshl_add_u64 v[64:65], v[64:65], 0, v[170:171]
	v_lshlrev_b64 v[64:65], 1, v[64:65]
	v_lshl_add_u64 v[66:67], s[8:9], 0, v[64:65]
	global_load_dwordx4 v[114:117], v[66:67], off
	v_lshl_add_u64 v[66:67], s[14:15], 0, v[64:65]
	global_load_dwordx4 v[118:121], v[66:67], off
	v_or_b32_e32 v64, 0x100, v64
	v_lshl_add_u64 v[66:67], s[8:9], 0, v[64:65]
	v_lshl_add_u64 v[64:65], s[14:15], 0, v[64:65]
	v_add_u32_e32 v134, 0xa0, v172
	global_load_dwordx4 v[122:125], v[66:67], off
	global_load_dwordx4 v[126:129], v[64:65], off
	v_ashrrev_i32_e32 v135, 31, v134
	v_lshlrev_b64 v[64:65], 10, v[134:135]
	v_lshl_add_u64 v[64:65], v[64:65], 0, v[170:171]
	v_lshlrev_b64 v[64:65], 1, v[64:65]
	v_lshl_add_u64 v[66:67], s[8:9], 0, v[64:65]
	global_load_dwordx4 v[92:95], v[66:67], off
	v_lshl_add_u64 v[66:67], s[14:15], 0, v[64:65]
	global_load_dwordx4 v[88:91], v[66:67], off
	v_or_b32_e32 v64, 0x100, v64
	v_lshl_add_u64 v[66:67], s[8:9], 0, v[64:65]
	v_lshl_add_u64 v[64:65], s[14:15], 0, v[64:65]
	global_load_dwordx4 v[84:87], v[66:67], off
	global_load_dwordx4 v[80:83], v[64:65], off
	v_lshlrev_b64 v[64:65], 10, v[96:97]
	v_lshl_add_u64 v[64:65], v[64:65], 0, v[170:171]
	v_lshlrev_b64 v[64:65], 1, v[64:65]
	v_lshl_add_u64 v[66:67], s[8:9], 0, v[64:65]
	global_load_dwordx4 v[76:79], v[66:67], off
	v_lshl_add_u64 v[66:67], s[14:15], 0, v[64:65]
	global_load_dwordx4 v[72:75], v[66:67], off
	v_or_b32_e32 v64, 0x100, v64
	v_lshl_add_u64 v[66:67], s[8:9], 0, v[64:65]
	v_lshl_add_u64 v[64:65], s[14:15], 0, v[64:65]
	global_load_dwordx4 v[68:71], v[66:67], off
	v_lshlrev_b64 v[130:131], 11, v[130:131]
	global_load_dwordx4 v[64:67], v[64:65], off
	s_waitcnt vmcnt(15)
	v_lshlrev_b32_e32 v136, 16, v98
	v_and_b32_e32 v137, 0xffff0000, v98
	s_waitcnt vmcnt(14)
	v_lshlrev_b32_e32 v138, 16, v102
	v_and_b32_e32 v139, 0xffff0000, v102
	v_lshlrev_b32_e32 v98, 16, v99
	v_and_b32_e32 v99, 0xffff0000, v99
	v_lshlrev_b32_e32 v102, 16, v103
	v_and_b32_e32 v103, 0xffff0000, v103
	v_pk_fma_f32 v[62:63], v[62:63], v[98:99], v[102:103]
	v_lshlrev_b32_e32 v98, 16, v100
	v_and_b32_e32 v99, 0xffff0000, v100
	v_lshlrev_b32_e32 v102, 16, v104
	v_and_b32_e32 v103, 0xffff0000, v104
	v_pk_fma_f32 v[60:61], v[60:61], v[136:137], v[138:139]
	v_pk_fma_f32 v[98:99], v[56:57], v[98:99], v[102:103]
	v_lshlrev_b32_e32 v56, 16, v101
	v_and_b32_e32 v57, 0xffff0000, v101
	v_lshlrev_b32_e32 v100, 16, v105
	v_and_b32_e32 v101, 0xffff0000, v105
	v_pk_fma_f32 v[100:101], v[58:59], v[56:57], v[100:101]
	v_cvt_pk_bf16_f32 v56, v60, v61
	v_lshl_add_u64 v[60:61], s[14:15], 0, v[130:131]
	v_cvt_pk_bf16_f32 v57, v62, v63
	v_cvt_pk_bf16_f32 v58, v98, v99
	v_cvt_pk_bf16_f32 v59, v100, v101
	v_lshl_add_u64 v[60:61], v[60:61], 0, v[168:169]
	global_store_dwordx4 v[60:61], v[56:59], off
	s_waitcnt vmcnt(14)
	s_nop 0
	v_lshlrev_b32_e32 v56, 16, v106
	v_and_b32_e32 v57, 0xffff0000, v106
	s_waitcnt vmcnt(13)
	v_lshlrev_b32_e32 v58, 16, v110
	v_and_b32_e32 v59, 0xffff0000, v110
	v_pk_fma_f32 v[52:53], v[52:53], v[56:57], v[58:59]
	v_lshlrev_b32_e32 v56, 16, v107
	v_and_b32_e32 v57, 0xffff0000, v107
	v_lshlrev_b32_e32 v58, 16, v111
	v_and_b32_e32 v59, 0xffff0000, v111
	v_pk_fma_f32 v[54:55], v[54:55], v[56:57], v[58:59]
	v_lshlrev_b32_e32 v56, 16, v108
	v_and_b32_e32 v57, 0xffff0000, v108
	v_lshlrev_b32_e32 v58, 16, v112
	v_and_b32_e32 v59, 0xffff0000, v112
	v_pk_fma_f32 v[56:57], v[48:49], v[56:57], v[58:59]
	v_lshlrev_b32_e32 v48, 16, v109
	v_and_b32_e32 v49, 0xffff0000, v109
	v_lshlrev_b32_e32 v58, 16, v113
	v_and_b32_e32 v59, 0xffff0000, v113
	v_pk_fma_f32 v[58:59], v[50:51], v[48:49], v[58:59]
	v_cvt_pk_bf16_f32 v48, v52, v53
	v_cvt_pk_bf16_f32 v49, v54, v55
	v_cvt_pk_bf16_f32 v50, v56, v57
	v_cvt_pk_bf16_f32 v51, v58, v59
	global_store_dwordx4 v[60:61], v[48:51], off offset:256
	s_waitcnt vmcnt(12)
	v_lshlrev_b32_e32 v52, 16, v118
	v_and_b32_e32 v53, 0xffff0000, v118
	v_lshlrev_b32_e32 v50, 16, v114
	v_and_b32_e32 v51, 0xffff0000, v114
	v_pk_fma_f32 v[44:45], v[44:45], v[50:51], v[52:53]
	v_lshlrev_b32_e32 v50, 16, v115
	v_and_b32_e32 v51, 0xffff0000, v115
	v_lshlrev_b32_e32 v52, 16, v119
	v_and_b32_e32 v53, 0xffff0000, v119
	v_pk_fma_f32 v[46:47], v[46:47], v[50:51], v[52:53]
	v_lshlrev_b32_e32 v50, 16, v116
	v_and_b32_e32 v51, 0xffff0000, v116
	v_lshlrev_b32_e32 v52, 16, v120
	v_and_b32_e32 v53, 0xffff0000, v120
	v_lshlrev_b64 v[48:49], 11, v[132:133]
	v_pk_fma_f32 v[50:51], v[40:41], v[50:51], v[52:53]
	v_lshlrev_b32_e32 v40, 16, v117
	v_and_b32_e32 v41, 0xffff0000, v117
	v_lshlrev_b32_e32 v52, 16, v121
	v_and_b32_e32 v53, 0xffff0000, v121
	v_pk_fma_f32 v[52:53], v[42:43], v[40:41], v[52:53]
	v_cvt_pk_bf16_f32 v40, v44, v45
	v_lshl_add_u64 v[44:45], s[14:15], 0, v[48:49]
	v_cvt_pk_bf16_f32 v41, v46, v47
	v_cvt_pk_bf16_f32 v42, v50, v51
	v_cvt_pk_bf16_f32 v43, v52, v53
	v_lshl_add_u64 v[44:45], v[44:45], 0, v[168:169]
	global_store_dwordx4 v[44:45], v[40:43], off
	s_waitcnt vmcnt(12)
	s_nop 0
	v_lshlrev_b32_e32 v40, 16, v122
	v_and_b32_e32 v41, 0xffff0000, v122
	s_waitcnt vmcnt(11)
	v_lshlrev_b32_e32 v42, 16, v126
	v_and_b32_e32 v43, 0xffff0000, v126
	v_pk_fma_f32 v[36:37], v[36:37], v[40:41], v[42:43]
	v_lshlrev_b32_e32 v40, 16, v123
	v_and_b32_e32 v41, 0xffff0000, v123
	v_lshlrev_b32_e32 v42, 16, v127
	v_and_b32_e32 v43, 0xffff0000, v127
	v_pk_fma_f32 v[38:39], v[38:39], v[40:41], v[42:43]
	v_lshlrev_b32_e32 v40, 16, v124
	v_and_b32_e32 v41, 0xffff0000, v124
	v_lshlrev_b32_e32 v42, 16, v128
	v_and_b32_e32 v43, 0xffff0000, v128
	v_pk_fma_f32 v[40:41], v[32:33], v[40:41], v[42:43]
	v_lshlrev_b32_e32 v32, 16, v125
	v_and_b32_e32 v33, 0xffff0000, v125
	v_lshlrev_b32_e32 v42, 16, v129
	v_and_b32_e32 v43, 0xffff0000, v129
	v_pk_fma_f32 v[42:43], v[34:35], v[32:33], v[42:43]
	v_cvt_pk_bf16_f32 v32, v36, v37
	v_cvt_pk_bf16_f32 v33, v38, v39
	v_cvt_pk_bf16_f32 v34, v40, v41
	v_cvt_pk_bf16_f32 v35, v42, v43
	global_store_dwordx4 v[44:45], v[32:35], off offset:256
	s_waitcnt vmcnt(10)
	v_lshlrev_b32_e32 v36, 16, v88
	v_and_b32_e32 v37, 0xffff0000, v88
	v_lshlrev_b32_e32 v34, 16, v92
	v_and_b32_e32 v35, 0xffff0000, v92
	v_pk_fma_f32 v[28:29], v[28:29], v[34:35], v[36:37]
	v_lshlrev_b32_e32 v34, 16, v93
	v_and_b32_e32 v35, 0xffff0000, v93
	v_lshlrev_b32_e32 v36, 16, v89
	v_and_b32_e32 v37, 0xffff0000, v89
	v_pk_fma_f32 v[30:31], v[30:31], v[34:35], v[36:37]
	v_lshlrev_b32_e32 v34, 16, v94
	v_and_b32_e32 v35, 0xffff0000, v94
	v_lshlrev_b32_e32 v36, 16, v90
	v_and_b32_e32 v37, 0xffff0000, v90
	v_lshlrev_b64 v[32:33], 11, v[134:135]
	v_pk_fma_f32 v[34:35], v[24:25], v[34:35], v[36:37]
	v_lshlrev_b32_e32 v24, 16, v95
	v_and_b32_e32 v25, 0xffff0000, v95
	v_lshlrev_b32_e32 v36, 16, v91
	v_and_b32_e32 v37, 0xffff0000, v91
	v_pk_fma_f32 v[36:37], v[26:27], v[24:25], v[36:37]
	v_cvt_pk_bf16_f32 v24, v28, v29
	v_lshl_add_u64 v[28:29], s[14:15], 0, v[32:33]
	v_cvt_pk_bf16_f32 v25, v30, v31
	v_cvt_pk_bf16_f32 v26, v34, v35
	v_cvt_pk_bf16_f32 v27, v36, v37
	v_lshl_add_u64 v[28:29], v[28:29], 0, v[168:169]
	global_store_dwordx4 v[28:29], v[24:27], off
	s_waitcnt vmcnt(10)
	s_nop 0
	v_lshlrev_b32_e32 v24, 16, v84
	v_and_b32_e32 v25, 0xffff0000, v84
	s_waitcnt vmcnt(9)
	v_lshlrev_b32_e32 v26, 16, v80
	v_and_b32_e32 v27, 0xffff0000, v80
	v_pk_fma_f32 v[20:21], v[20:21], v[24:25], v[26:27]
	v_lshlrev_b32_e32 v24, 16, v85
	v_and_b32_e32 v25, 0xffff0000, v85
	v_lshlrev_b32_e32 v26, 16, v81
	v_and_b32_e32 v27, 0xffff0000, v81
	v_pk_fma_f32 v[22:23], v[22:23], v[24:25], v[26:27]
	v_lshlrev_b32_e32 v24, 16, v86
	v_and_b32_e32 v25, 0xffff0000, v86
	v_lshlrev_b32_e32 v26, 16, v82
	v_and_b32_e32 v27, 0xffff0000, v82
	v_pk_fma_f32 v[24:25], v[16:17], v[24:25], v[26:27]
	v_lshlrev_b32_e32 v16, 16, v87
	v_and_b32_e32 v17, 0xffff0000, v87
	v_lshlrev_b32_e32 v26, 16, v83
	v_and_b32_e32 v27, 0xffff0000, v83
	v_pk_fma_f32 v[26:27], v[18:19], v[16:17], v[26:27]
	v_cvt_pk_bf16_f32 v16, v20, v21
	v_cvt_pk_bf16_f32 v17, v22, v23
	v_cvt_pk_bf16_f32 v18, v24, v25
	v_cvt_pk_bf16_f32 v19, v26, v27
	global_store_dwordx4 v[28:29], v[16:19], off offset:256
	s_waitcnt vmcnt(8)
	v_lshlrev_b32_e32 v20, 16, v72
	v_and_b32_e32 v21, 0xffff0000, v72
	v_lshlrev_b32_e32 v18, 16, v76
	v_and_b32_e32 v19, 0xffff0000, v76
	v_pk_fma_f32 v[12:13], v[12:13], v[18:19], v[20:21]
	v_lshlrev_b32_e32 v18, 16, v77
	v_and_b32_e32 v19, 0xffff0000, v77
	v_lshlrev_b32_e32 v20, 16, v73
	v_and_b32_e32 v21, 0xffff0000, v73
	v_pk_fma_f32 v[14:15], v[14:15], v[18:19], v[20:21]
	v_lshlrev_b32_e32 v18, 16, v78
	v_and_b32_e32 v19, 0xffff0000, v78
	v_lshlrev_b32_e32 v20, 16, v74
	v_and_b32_e32 v21, 0xffff0000, v74
	v_lshlrev_b64 v[16:17], 11, v[96:97]
	v_pk_fma_f32 v[18:19], v[8:9], v[18:19], v[20:21]
	v_lshlrev_b32_e32 v8, 16, v79
	v_and_b32_e32 v9, 0xffff0000, v79
	v_lshlrev_b32_e32 v20, 16, v75
	v_and_b32_e32 v21, 0xffff0000, v75
	v_pk_fma_f32 v[20:21], v[10:11], v[8:9], v[20:21]
	v_cvt_pk_bf16_f32 v8, v12, v13
	v_lshl_add_u64 v[12:13], s[14:15], 0, v[16:17]
	v_cvt_pk_bf16_f32 v9, v14, v15
	v_cvt_pk_bf16_f32 v10, v18, v19
	v_cvt_pk_bf16_f32 v11, v20, v21
	v_lshl_add_u64 v[12:13], v[12:13], 0, v[168:169]
	global_store_dwordx4 v[12:13], v[8:11], off
	s_waitcnt vmcnt(8)
	s_nop 0
	v_lshlrev_b32_e32 v8, 16, v68
	v_and_b32_e32 v9, 0xffff0000, v68
	s_waitcnt vmcnt(7)
	v_lshlrev_b32_e32 v10, 16, v64
	v_and_b32_e32 v11, 0xffff0000, v64
	v_pk_fma_f32 v[4:5], v[4:5], v[8:9], v[10:11]
	v_lshlrev_b32_e32 v8, 16, v69
	v_and_b32_e32 v9, 0xffff0000, v69
	v_lshlrev_b32_e32 v10, 16, v65
	v_and_b32_e32 v11, 0xffff0000, v65
	v_pk_fma_f32 v[6:7], v[6:7], v[8:9], v[10:11]
	v_lshlrev_b32_e32 v8, 16, v70
	v_and_b32_e32 v9, 0xffff0000, v70
	v_lshlrev_b32_e32 v10, 16, v66
	v_and_b32_e32 v11, 0xffff0000, v66
	v_pk_fma_f32 v[8:9], v[0:1], v[8:9], v[10:11]
	v_lshlrev_b32_e32 v0, 16, v71
	v_and_b32_e32 v1, 0xffff0000, v71
	v_lshlrev_b32_e32 v10, 16, v67
	v_and_b32_e32 v11, 0xffff0000, v67
	v_pk_fma_f32 v[10:11], v[2:3], v[0:1], v[10:11]
	v_cvt_pk_bf16_f32 v0, v4, v5
	v_cvt_pk_bf16_f32 v1, v6, v7
	v_cvt_pk_bf16_f32 v2, v8, v9
	v_cvt_pk_bf16_f32 v3, v10, v11
	global_store_dwordx4 v[12:13], v[0:3], off offset:256
	s_cbranch_vccnz .LBB0_1371
	s_andn2_b64 vcc, exec, s[12:13]
	s_cbranch_vccnz .LBB0_1370
	s_barrier
	s_branch .LBB0_1370
